# code placement: one pad instruction before the GEMM phase so the K-loop head sits at the baseline byte phase (mod 256)
# baseline (speedup 1.0000x reference)
.LBB0_559:
	s_nop 0
	s_and_b64 vcc, exec, s[0:1]
	s_cbranch_vccz .LBB0_664
	s_mov_b64 s[4:5], s[36:37]
	s_load_dwordx2 s[14:15], s[4:5], 0xa8
	s_mov_b64 s[8:9], -1
	s_mov_b64 s[10:11], 0
	s_cmp_lt_i32 s63, 5
	s_mov_b64 s[6:7], 0
	s_cbranch_scc1 .LBB0_566
	s_cmp_gt_i32 s63, 6
	s_cbranch_scc0 .LBB0_569
	s_cmp_eq_u32 s63, 7
	s_mov_b64 s[6:7], -1
	s_cbranch_scc0 .LBB0_564
	s_mov_b64 s[6:7], 0
